# SSD: wave-0 dt cumulative scan for next chunk moved from end of segment C to end of segment B (branch-free offset select)
# speedup vs baseline: 1.0192x; 1.0035x over previous
; __device__ __forceinline__ unsigned f2bf(float f) { return pk2(f, f) & 0xffffu; }
; template <bool DRY> __device__ __forceinline__ void ssd_unit(const Args& A, char* lds, int b, int h) {
;     ...
;         for (int r = 0; r < 4; ++r) { const int l = lt * 16 + 4 * fq + r; const float al = DTA[64 + l];
; #pragma unroll
;             for (int si = 0; si < 2; ++si) { const int s = (st0 + si) * 16 + fr; const float v = (s <= l) ? cb[si][r] * __expf(al - DTA[64 + s]) : 0.f; GG[l * 72 + s] = (bf16)f2bf(v); }
;             const float ea = DTA[128 + l]; ya[0][r] *= ea; ya[1][r] *= ea; }
;         const float decay = __expf(DTA[64 + 63]);
;         BAR_LDS();
; #pragma unroll
;         for (int ks = 0; ks < 2; ++ks) { const bf16x8 gf = *(const bf16x8*)(GG + (lt * 16 + fr) * 72 + ks * 32 + 8 * fq);
; #pragma unroll
;             for (int pi = 0; pi < 2; ++pi) { const int p = (pt0 + pi) * 16 + fr; const bf16x8 xf = *(const bf16x8*)(XT + p * 72 + (((ks * 4 + fq) ^ ((p >> 3) & 7)) << 3)); ya[pi] = __builtin_amdgcn_mfma_f32_16x16x32_bf16(gf, xf, ya[pi], 0, 0, 0); } }
; #pragma unroll
;         for (int pi = 0; pi < 2; ++pi)
; #pragma unroll
;             for (int ni = 0; ni < 2; ++ni) sta[pi][ni] = sta[pi][ni] * decay;
; #pragma unroll
;         for (int ks = 0; ks < 2; ++ks) { bf16x8 bt[2];
; #pragma unroll
;             for (int ni = 0; ni < 2; ++ni) { const int n = (nt0 + ni) * 16 + fr; bt[ni] = *(const bf16x8*)(BST + n * 72 + (((ks * 4 + fq) ^ ((n >> 3) & 7)) << 3)); }
; #pragma unroll
;             for (int pi = 0; pi < 2; ++pi) { const int p = (pt0 + pi) * 16 + fr; const bf16x8 xw = *(const bf16x8*)(XWT + p * 72 + (((ks * 4 + fq) ^ ((p >> 3) & 7)) << 3));
; #pragma unroll
;                 for (int ni = 0; ni < 2; ++ni) sta[pi][ni] = __builtin_amdgcn_mfma_f32_16x16x32_bf16(xw, bt[ni], sta[pi][ni], 0, 0, 0); } }
; #pragma unroll
;         for (int pi = 0; pi < 2; ++pi)
; #pragma unroll
;             for (int ni = 0; ni < 2; ++ni)
; #pragma unroll
;                 for (int r = 0; r < 4; ++r) SBF[((pt0 + pi) * 16 + 4 * fq + r) * 136 + (nt0 + ni) * 16 + fr] = (bf16)f2bf(sta[pi][ni][r]);
; #pragma unroll
;         for (int pi = 0; pi < 2; ++pi)
; #pragma unroll
;             for (int r = 0; r < 4; ++r) { const int l = lt * 16 + 4 * fq + r, p = (pt0 + pi) * 16 + fr;
;                 const float y = ya[pi][r] + Dh * bf2f(XS[l * 72 + p]);
.LBB0_837:
	s_or_b64 exec, exec, s[66:67]
	ds_write_b16 v119, v44
	v_mov_b32_e32 v44, s4
	ds_read_b32 v50, v85 offset:524
	ds_read_b32 v51, v44 offset:508
	s_and_b64 s[98:99], exec, s[26:27]
	s_cbranch_scc1 .Lssd_dts_skip
	v_mul_f32_e64 v190, v69, -v100
	v_mov_b32_e32 v191, 0
	s_nop 1
	v_mov_b32_dpp v191, v190 row_shr:1 row_mask:0xf bank_mask:0xf
	v_fma_f32 v190, v69, -v100, v191
	v_cvt_f32_u32_e32 v192, v98
	s_nop 0
	v_add_f32_dpp v190, v190, v190 row_shr:2 row_mask:0xf bank_mask:0xf bound_ctrl:1
	v_min_f32_e32 v193, 1.0, v192
	v_add_f32_e32 v194, -1.0, v192
	v_add_f32_dpp v190, v190, v190 row_shr:4 row_mask:0xf bank_mask:0xf bound_ctrl:1
	v_add_f32_e32 v195, -2.0, v192
	v_med3_f32 v194, v194, 0, 1.0
	v_add_f32_dpp v190, v190, v190 row_shr:8 row_mask:0xf bank_mask:0xf bound_ctrl:1
	v_med3_f32 v195, v195, 0, 1.0
	s_nop 0
	v_readlane_b32 s98, v190, 15
	v_readlane_b32 s99, v190, 31
	v_readlane_b32 s100, v190, 47
	v_mul_f32_e32 v191, s98, v193
	v_fma_f32 v191, v194, s99, v191
	v_fma_f32 v191, v195, s100, v191
	v_add_f32_e32 v190, v190, v191
	v_mul_f32_e32 v191, 0x3fb8aa3b, v190
	v_readlane_b32 s98, v190, 63
	v_exp_f32_e32 v191, v191
	s_and_b32 s99, s0, 0x100
	v_sub_f32_e32 v192, s98, v190
	v_mul_f32_e32 v192, 0x3fb8aa3b, v192
	v_exp_f32_e32 v192, v192
	v_lshl_add_u32 v193, s99, 2, v126
	ds_write2st64_b32 v193, v69, v190 offset1:1
	ds_write2st64_b32 v193, v191, v192 offset0:2 offset1:3
	s_cmp_gt_u32 s1, 28
	s_cbranch_scc1 .Lssd_dts_skip
	global_load_dword v69, v[74:75], off
.Lssd_dts_skip:
	s_waitcnt lgkmcnt(0)
	s_barrier
	s_waitcnt lgkmcnt(0)
	v_mul_f32_e32 v42, v42, v49
	v_mul_f32_e32 v38, v38, v49
	ds_read_b128 v[46:49], v113
	ds_read_b128 v[88:91], v106 offset:53248
	ds_read_b128 v[150:153], v104 offset:53248
	ds_read_b128 v[154:157], v113 offset:64
	ds_read_b128 v[158:161], v106 offset:62464
	v_mul_f32_e32 v41, v41, v45
	v_mul_f32_e32 v37, v37, v45
	v_mul_f32_e32 v40, v40, v83
	v_mul_f32_e32 v36, v36, v83
	v_mul_f32_e32 v43, v43, v50
	v_mul_f32_e32 v39, v39, v50
	v_mul_f32_e32 v82, 0x3fb8aa3b, v51
	s_waitcnt lgkmcnt(0)
	v_mfma_f32_16x16x32_bf16 v[40:43], v[46:49], v[88:91], v[40:43]
	ds_read_b128 v[88:91], v102 offset:53248
	ds_read_b128 v[162:165], v104 offset:62464
	v_exp_f32_e32 v82, v82
	v_add_u32_e32 v141, v127, v135
	v_mfma_f32_16x16x32_bf16 v[44:47], v[46:49], v[150:153], v[36:39]
	ds_read_b128 v[48:51], v101 offset:53248
	ds_read_b128 v[150:153], v102 offset:62464
	v_pk_mul_f32 v[14:15], v[14:15], v[82:83] op_sel_hi:[1,0]
	v_pk_mul_f32 v[12:13], v[12:13], v[82:83] op_sel_hi:[1,0]
	s_waitcnt lgkmcnt(0)
	v_mfma_f32_16x16x32_bf16 v[36:39], v[154:157], v[88:91], v[40:43]
	ds_read_b128 v[88:91], v103 offset:34816
	ds_read_b128 v[166:169], v101 offset:62464
	v_pk_mul_f32 v[10:11], v[10:11], v[82:83] op_sel_hi:[1,0]
	v_pk_mul_f32 v[8:9], v[8:9], v[82:83] op_sel_hi:[1,0]
	v_mfma_f32_16x16x32_bf16 v[40:43], v[154:157], v[48:51], v[44:47]
	v_mul_f32_e64 v6, v6, v82
	v_mul_f32_e64 v7, v7, v82
	v_pk_mul_f32 v[4:5], v[4:5], v[82:83] op_sel_hi:[1,0]
	v_pk_mul_f32 v[2:3], v[2:3], v[82:83] op_sel_hi:[1,0]
	ds_read_b128 v[44:47], v118 offset:34816
	s_waitcnt lgkmcnt(0)
	v_mfma_f32_16x16x32_bf16 v[12:15], v[158:161], v[88:91], v[12:15]
	v_mul_f32_e64 v0, v0, v82
	v_mul_f32_e64 v1, v1, v82
	v_add_u32_e32 v143, v128, v135
	v_add_u32_e32 v144, v127, v136
	v_mfma_f32_16x16x32_bf16 v[8:11], v[158:161], v[44:47], v[8:11]
	v_add_u32_e32 v140, v128, v136
	s_add_i32 s1, s1, 1
	v_mfma_f32_16x16x32_bf16 v[4:7], v[162:165], v[44:47], v[4:7]
	ds_read_b128 v[44:47], v121 offset:34816
	ds_read_b128 v[48:51], v122 offset:34816
	v_mfma_f32_16x16x32_bf16 v[0:3], v[162:165], v[88:91], v[0:3]
	v_lshlrev_b32_e32 v88, 16, v86
	v_and_b32_e32 v89, 0xffff0000, v86
	s_waitcnt lgkmcnt(0)
	v_mfma_f32_16x16x32_bf16 v[12:15], v[150:153], v[44:47], v[12:15]
	v_mfma_f32_16x16x32_bf16 v[8:11], v[150:153], v[48:51], v[8:11]
	v_mfma_f32_16x16x32_bf16 v[0:3], v[166:169], v[44:47], v[0:3]
	s_nop 5
	v_cvt_pk_bf16_f32 v44, v12, s0
	ds_write_b16 v141, v44
	v_cvt_pk_bf16_f32 v44, v13, s0
	ds_write_b16 v141, v44 offset:272
	v_cvt_pk_bf16_f32 v44, v14, s0
	ds_write_b16 v141, v44 offset:544
	v_cvt_pk_bf16_f32 v44, v15, s0
	ds_write_b16 v141, v44 offset:816
	v_cvt_pk_bf16_f32 v44, v8, s0
	ds_write_b16 v143, v44
	v_cvt_pk_bf16_f32 v44, v9, s0
	ds_write_b16 v143, v44 offset:272
	v_cvt_pk_bf16_f32 v44, v10, s0
	ds_write_b16 v143, v44 offset:544
	v_cvt_pk_bf16_f32 v44, v11, s0
	v_mfma_f32_16x16x32_bf16 v[4:7], v[166:169], v[48:51], v[4:7]
	ds_write_b16 v143, v44 offset:816
	v_cvt_pk_bf16_f32 v44, v0, s0
	ds_write_b16 v144, v44
	v_cvt_pk_bf16_f32 v44, v1, s0
	ds_write_b16 v144, v44 offset:272
	v_cvt_pk_bf16_f32 v44, v2, s0
	ds_write_b16 v144, v44 offset:544
	v_cvt_pk_bf16_f32 v44, v3, s0
	ds_write_b16 v144, v44 offset:816
	v_cvt_pk_bf16_f32 v44, v4, s0
	ds_write_b16 v140, v44
	v_cvt_pk_bf16_f32 v44, v5, s0
	ds_write_b16 v140, v44 offset:272
	v_cvt_pk_bf16_f32 v44, v6, s0
	ds_write_b16 v140, v44 offset:544
	v_cvt_pk_bf16_f32 v44, v7, s0
	v_lshlrev_b32_e32 v45, 16, v97
	ds_write_b16 v140, v44 offset:816
	v_mul_f32_e32 v44, 0xbfb8aa3b, v45
	v_exp_f32_e32 v44, v44
	ds_read_u16 v46, v110
	ds_read_u16 v47, v110 offset:144
	ds_read_u16 v48, v110 offset:288
	ds_read_u16 v97, v110 offset:432
	ds_read_u16 v82, v105
	ds_read_u16 v87, v105 offset:144
	ds_read_u16 v90, v105 offset:288
	ds_read_u16 v93, v105 offset:432
	s_waitcnt lgkmcnt(0)
; __device__ __forceinline__ unsigned f2bf(float f) { return pk2(f, f) & 0xffffu; }
; __device__ __forceinline__ float bf2f(unsigned short h) { return __uint_as_float(((unsigned)h) << 16); }
; __device__ __forceinline__ float row_sum16(float v) { v += dppf<0xB1>(v, v); v += dppf<0x4E>(v, v); v += dppf<0x141>(v, v); v += dppf<0x140>(v, v); return v; }
; __device__ __forceinline__ float silu_f(float x) { return x * __builtin_amdgcn_rcpf(1.f + __expf(-x)); }
; template <bool DRY> __device__ __forceinline__ void ssd_unit(const Args& A, char* lds, int b, int h) {
;     ...
;         for (int pi = 0; pi < 2; ++pi)
; #pragma unroll
;             for (int r = 0; r < 4; ++r) { const int l = lt * 16 + 4 * fq + r, p = (pt0 + pi) * 16 + fr;
;                 const float y = ya[pi][r] + Dh * bf2f(XS[l * 72 + p]);
;                 const float z = bf2f(zv[pi][r]); const float gt = y * silu_f(z);
;                 gts[pi][r] = (unsigned short)f2bf(gt); sqs[pi][r] = row_sum16(gt * gt); }
	v_lshlrev_b32_e32 v46, 16, v46
	v_fma_f32 v36, v54, v46, v36
	v_add_f32_e32 v44, 1.0, v44
	v_rcp_f32_e32 v46, v44
	v_lshlrev_b32_e32 v44, 16, v84
	v_mul_f32_e32 v49, 0xbfb8aa3b, v44
	v_exp_f32_e32 v49, v49
	v_mul_f32_e32 v45, v46, v45
	v_mul_f32_e32 v36, v45, v36
	v_and_b32_e32 v45, 0xffff0000, v84
	v_add_f32_e32 v46, 1.0, v49
	v_mul_f32_e32 v49, 0xbfb8aa3b, v45
	v_exp_f32_e32 v50, v49
	v_lshlrev_b32_e32 v49, 16, v48
	v_lshlrev_b32_e32 v48, 16, v47
	v_rcp_f32_e32 v46, v46
	v_add_f32_e32 v47, 1.0, v50
	v_rcp_f32_e32 v47, v47
	v_mov_b32_e32 v50, v37
	v_mov_b32_e32 v51, v38
	v_pk_fma_f32 v[48:49], v[54:55], v[48:49], v[50:51]
	v_pk_mul_f32 v[44:45], v[46:47], v[44:45]
	v_lshlrev_b32_e32 v91, 16, v90
	v_pk_mul_f32 v[44:45], v[44:45], v[48:49]
	v_lshlrev_b32_e32 v90, 16, v87
	v_pk_mov_b32 v[46:47], v[44:45], v[44:45] op_sel:[1,0]
	s_nop 0
	v_mov_b32_e32 v37, v47
	v_pk_mul_f32 v[48:49], v[36:37], v[36:37]
	v_lshlrev_b32_e32 v47, 16, v82
	v_fma_f32 v40, v54, v47, v40
	v_mov_b32_dpp v48, v48 quad_perm:[1,0,3,2] row_mask:0xf bank_mask:0xf
	v_mov_b32_dpp v49, v49 quad_perm:[1,0,3,2] row_mask:0xf bank_mask:0xf
	v_pk_fma_f32 v[48:49], v[36:37], v[36:37], v[48:49]
	v_lshlrev_b32_e32 v37, 16, v96
	v_mul_f32_e32 v38, 0xbfb8aa3b, v37
	v_exp_f32_e32 v38, v38
	v_mov_b32_e32 v50, v48
	v_mov_b32_e32 v51, v49
	v_add_f32_e32 v38, 1.0, v38
	v_rcp_f32_e32 v38, v38
	v_mov_b32_dpp v50, v50 quad_perm:[2,3,0,1] row_mask:0xf bank_mask:0xf
	v_mov_b32_dpp v51, v51 quad_perm:[2,3,0,1] row_mask:0xf bank_mask:0xf
	v_pk_add_f32 v[48:49], v[48:49], v[50:51]
	v_mul_f32_e32 v37, v38, v37
	v_mul_f32_e32 v47, v37, v40
	v_mul_f32_e32 v37, 0xbfb8aa3b, v88
	v_exp_f32_e32 v37, v37
	v_mul_f32_e32 v38, 0xbfb8aa3b, v89
	v_exp_f32_e32 v38, v38
	v_mov_b32_e32 v40, v41
	v_add_f32_e32 v37, 1.0, v37
	v_rcp_f32_e32 v86, v37
	v_add_f32_e32 v37, 1.0, v38
	v_rcp_f32_e32 v87, v37
	v_mov_b32_e32 v41, v42
	v_pk_fma_f32 v[40:41], v[54:55], v[90:91], v[40:41]
	v_mov_b32_e32 v42, v39
	v_pk_mul_f32 v[86:87], v[86:87], v[88:89]
	v_pk_mul_f32 v[82:83], v[46:47], v[46:47]
	v_pk_mul_f32 v[86:87], v[86:87], v[40:41]
	v_mov_b32_e32 v50, v48
	v_pk_mul_f32 v[40:41], v[86:87], v[86:87]
	v_mov_b32_dpp v82, v82 quad_perm:[1,0,3,2] row_mask:0xf bank_mask:0xf
	v_mov_b32_dpp v83, v83 quad_perm:[1,0,3,2] row_mask:0xf bank_mask:0xf
	v_mov_b32_dpp v40, v40 quad_perm:[1,0,3,2] row_mask:0xf bank_mask:0xf
	v_mov_b32_dpp v41, v41 quad_perm:[1,0,3,2] row_mask:0xf bank_mask:0xf
	v_pk_fma_f32 v[40:41], v[86:87], v[86:87], v[40:41]
	v_pk_fma_f32 v[82:83], v[46:47], v[46:47], v[82:83]
	v_mov_b32_e32 v88, v40
	v_mov_b32_e32 v89, v41
	v_mov_b32_e32 v84, v82
	v_mov_b32_dpp v88, v88 quad_perm:[2,3,0,1] row_mask:0xf bank_mask:0xf
	v_mov_b32_dpp v89, v89 quad_perm:[2,3,0,1] row_mask:0xf bank_mask:0xf
	v_pk_add_f32 v[40:41], v[40:41], v[88:89]
	v_mov_b32_e32 v85, v83
	v_mov_b32_e32 v88, v40
	v_mov_b32_e32 v89, v41
	v_mov_b32_dpp v84, v84 quad_perm:[2,3,0,1] row_mask:0xf bank_mask:0xf
	v_mov_b32_dpp v88, v88 row_half_mirror row_mask:0xf bank_mask:0xf
	v_mov_b32_dpp v89, v89 row_half_mirror row_mask:0xf bank_mask:0xf
	v_pk_add_f32 v[88:89], v[40:41], v[88:89]
	v_lshlrev_b32_e32 v40, 16, v94
	v_mul_f32_e32 v37, 0xbfb8aa3b, v40
	v_lshlrev_b32_e32 v41, 16, v95
	v_exp_f32_e32 v37, v37
	v_mul_f32_e32 v38, 0xbfb8aa3b, v41
	v_exp_f32_e32 v38, v38
	v_lshlrev_b32_e32 v95, 16, v93
	v_add_f32_e32 v37, 1.0, v37
	v_rcp_f32_e32 v92, v37
	v_add_f32_e32 v37, 1.0, v38
	v_rcp_f32_e32 v93, v37
	v_lshlrev_b32_e32 v94, 16, v97
	v_pk_fma_f32 v[38:39], v[54:55], v[94:95], v[42:43]
	v_mov_b32_dpp v85, v85 quad_perm:[2,3,0,1] row_mask:0xf bank_mask:0xf
	v_pk_mul_f32 v[40:41], v[92:93], v[40:41]
	v_pk_add_f32 v[82:83], v[82:83], v[84:85]
	v_pk_mul_f32 v[92:93], v[40:41], v[38:39]
	v_mov_b32_e32 v51, v49
	v_pk_mul_f32 v[38:39], v[92:93], v[92:93]
	v_mov_b32_e32 v84, v82
	v_mov_b32_e32 v85, v83
	v_mov_b32_dpp v38, v38 quad_perm:[1,0,3,2] row_mask:0xf bank_mask:0xf
	v_mov_b32_dpp v39, v39 quad_perm:[1,0,3,2] row_mask:0xf bank_mask:0xf
	v_pk_fma_f32 v[38:39], v[92:93], v[92:93], v[38:39]
	v_mov_b32_dpp v50, v50 row_half_mirror row_mask:0xf bank_mask:0xf
	v_mov_b32_e32 v40, v38
	v_mov_b32_e32 v41, v39
	v_mov_b32_dpp v51, v51 row_half_mirror row_mask:0xf bank_mask:0xf
	v_mov_b32_dpp v40, v40 quad_perm:[2,3,0,1] row_mask:0xf bank_mask:0xf
	v_mov_b32_dpp v41, v41 quad_perm:[2,3,0,1] row_mask:0xf bank_mask:0xf
	v_pk_add_f32 v[38:39], v[38:39], v[40:41]
	v_mov_b32_dpp v84, v84 row_half_mirror row_mask:0xf bank_mask:0xf
	v_mov_b32_e32 v40, v38
	v_mov_b32_e32 v41, v39
	v_mov_b32_dpp v85, v85 row_half_mirror row_mask:0xf bank_mask:0xf
	v_mov_b32_dpp v40, v40 row_half_mirror row_mask:0xf bank_mask:0xf
	v_mov_b32_dpp v41, v41 row_half_mirror row_mask:0xf bank_mask:0xf
	v_pk_add_f32 v[48:49], v[48:49], v[50:51]
	v_pk_add_f32 v[82:83], v[82:83], v[84:85]
	v_pk_add_f32 v[94:95], v[38:39], v[40:41]
	v_mov_b32_e32 v50, v48
	v_mov_b32_e32 v51, v49
	v_mov_b32_e32 v84, v82
	v_mov_b32_e32 v85, v83
	v_mov_b32_e32 v90, v88
	v_mov_b32_e32 v91, v89
	v_mov_b32_e32 v96, v94
	v_mov_b32_e32 v97, v95
	v_mov_b32_dpp v50, v50 row_mirror row_mask:0xf bank_mask:0xf
	v_mov_b32_dpp v51, v51 row_mirror row_mask:0xf bank_mask:0xf
	v_mov_b32_dpp v84, v84 row_mirror row_mask:0xf bank_mask:0xf
	v_mov_b32_dpp v85, v85 row_mirror row_mask:0xf bank_mask:0xf
	v_mov_b32_dpp v90, v90 row_mirror row_mask:0xf bank_mask:0xf
	v_mov_b32_dpp v91, v91 row_mirror row_mask:0xf bank_mask:0xf
	v_mov_b32_dpp v96, v96 row_mirror row_mask:0xf bank_mask:0xf
	v_mov_b32_dpp v97, v97 row_mirror row_mask:0xf bank_mask:0xf
; __device__ __forceinline__ unsigned f2bf(float f) { return pk2(f, f) & 0xffffu; }
; __device__ __forceinline__ float bf2f(unsigned short h) { return __uint_as_float(((unsigned)h) << 16); }
; __device__ __forceinline__ float rdlane(float v, int l) { return __builtin_bit_cast(float, __builtin_amdgcn_readlane(__builtin_bit_cast(int, v), l)); }
; #define BAR_LDS() asm volatile("s_waitcnt lgkmcnt(0)\n\ts_barrier" ::: "memory")
; template <bool DRY> __device__ __forceinline__ void ssd_unit(const Args& A, char* lds, int b, int h) {
;     ...
;         { const int t = tid >> 4, c8 = tid & 15;
;           *(bf16x8*)(BS + t * 136 + c8 * 8) = pre[0]; *(bf16x8*)(BS + (t + 32) * 136 + c8 * 8) = pre[1]; *(bf16x8*)(CS + t * 136 + c8 * 8) = pre[2]; *(bf16x8*)(CS + (t + 32) * 136 + c8 * 8) = pre[3];
;           const int sw0 = ((((t >> 3) ^ (c8 & 7)) << 3) + (t & 7)), sw1 = (((((t + 32) >> 3) ^ (c8 & 7)) << 3) + (t & 7));
; #pragma unroll
;           for (int e = 0; e < 8; ++e) { BST[(c8 * 8 + e) * 72 + sw0] = (bf16)pre[0][e]; BST[(c8 * 8 + e) * 72 + sw1] = (bf16)pre[1][e]; }
;           const int tx = tid >> 3, cx = tid & 7; *(bf16x8*)(XS + tx * 72 + cx * 8) = pre[4]; const float dtv = DTA[tx], wv = DTA[192 + tx]; const int sx = ((((tx >> 3) ^ cx) << 3) + (tx & 7));
; #pragma unroll
;           for (int e = 0; e < 8; ++e) { const float xd = bf2f((unsigned short)pre[4][e]) * dtv; XT[(cx * 8 + e) * 72 + sx] = (bf16)f2bf(xd); XWT[(cx * 8 + e) * 72 + sx] = (bf16)f2bf(xd * wv); } }
;         if (c > 0) {
; #pragma unroll
;             for (int pi = 0; pi < 2; ++pi)
; #pragma unroll
;                 for (int r = 0; r < 4; ++r) { const int l = lt * 16 + 4 * fq + r;
;                     if (!DRY || sqs[pi][r] == 1.2345e30f) { ((bf16*)pZ)[((size_t)(c - 1) * 64 + r) * LD0 + 16 * pi] = gts[pi][r];
;                         if (fr == 0) ((float*)((unsigned char*)A.out + (m0 - 64 + l) * 4096 + 3072))[h * 4 + pt0 + pi] = sqs[pi][r]; } } }
;     ...
;         if (wave == 0 && c + 1 < SEQL / 64) { float* DN = DTA0 + ((c + 1) & 1) * 256; const float s = wave_scan(Ah * dtn, lane); const float tot = rdlane(s, 63);
;             DN[lane] = dtn; DN[64 + lane] = s; DN[128 + lane] = __expf(s); DN[192 + lane] = __expf(tot - s);
;             if (c + 2 < SEQL / 64) dtn = DT[(m0 + 128 + lane) * 16 + h]; }
;         BAR_LDS();
.LBB0_846:
	s_waitcnt lgkmcnt(0)
	s_barrier
	v_cvt_pk_bf16_f32 v151, v36, s0
	v_pk_add_f32 v[42:43], v[48:49], v[50:51]
	v_cvt_pk_bf16_f32 v149, v47, s0
	v_pk_add_f32 v[40:41], v[82:83], v[84:85]
	v_cvt_pk_bf16_f32 v82, v92, s0
	v_cvt_pk_bf16_f32 v50, v93, s0
	s_addk_i32 s0, 0x100
	v_cvt_pk_bf16_f32 v150, v44, v45
	v_cvt_pk_bf16_f32 v51, v86, v87
	v_pk_add_f32 v[38:39], v[88:89], v[90:91]
	v_pk_add_f32 v[36:37], v[94:95], v[96:97]
	s_waitcnt vmcnt(0)
	v_perm_b32 v86, v147, v148, s3
	v_perm_b32 v84, v146, v145, s3
	v_lshl_add_u64 v[72:73], v[72:73], 0, s[60:61]
	v_lshl_add_u64 v[74:75], v[74:75], 0, s[62:63]
	v_lshl_add_u64 v[76:77], v[76:77], 0, s[64:65]
	v_lshl_add_u64 v[78:79], v[78:79], 0, s[64:65]
	s_cmp_eq_u32 s1, 30
	v_lshl_add_u64 v[80:81], v[80:81], 0, s[64:65]
	s_cbranch_scc1 .LBB0_852
	v_mov_b32_e32 v94, v129
	v_mov_b32_e32 v97, v131
	v_mov_b32_e32 v96, v130
	v_mov_b32_e32 v95, v67
	s_branch .LBB0_811
.LBB0_852:
	ds_write_b128 v120, v[20:23] offset:17408
	ds_write_b128 v132, v[24:27] offset:17408
	ds_write_b128 v120, v[28:31]
	ds_write_b128 v132, v[32:35]
	ds_write_b16 v123, v20 offset:34816
	ds_write_b16 v124, v24 offset:34816
	ds_write_b16_d16_hi v123, v20 offset:34960
	ds_write_b16_d16_hi v124, v24 offset:34960
	ds_write_b16 v123, v21 offset:35104
	ds_write_b16 v124, v25 offset:35104
	ds_write_b16_d16_hi v123, v21 offset:35248
	ds_write_b16_d16_hi v124, v25 offset:35248
	ds_write_b16 v123, v22 offset:35392
	ds_write_b16 v124, v26 offset:35392
	ds_write_b16_d16_hi v123, v22 offset:35536
	ds_write_b16_d16_hi v124, v26 offset:35536
	ds_write_b16 v123, v23 offset:35680
	ds_write_b16 v124, v27 offset:35680
	ds_write_b16_d16_hi v123, v23 offset:35824
	ds_write_b16_d16_hi v124, v27 offset:35824
	ds_write_b128 v117, v[16:19]
	v_lshl_add_u32 v20, v66, 2, 0
	v_add_u32_e32 v20, 0x1a800, v20
	ds_read2st64_b32 v[20:21], v20 offset1:3
	v_lshlrev_b32_e32 v22, 16, v16
	v_and_b32_e32 v16, 0xffff0000, v16
	s_mov_b32 s25, 0
	s_or_b32 s24, s36, 0x780
	s_waitcnt lgkmcnt(0)
	v_mul_f32_e32 v22, v20, v22
	v_cvt_pk_bf16_f32 v23, v22, s0
	v_mul_f32_e32 v22, v21, v22
	v_cvt_pk_bf16_f32 v22, v22, s0
	v_mul_f32_e32 v16, v20, v16
	ds_write_b16 v109, v22 offset:62464
	v_cvt_pk_bf16_f32 v22, v16, s0
	v_mul_f32_e32 v16, v21, v16
	v_cvt_pk_bf16_f32 v16, v16, s0
	ds_write_b16 v109, v16 offset:62608
	v_lshlrev_b32_e32 v16, 16, v17
	v_mul_f32_e32 v16, v20, v16
	ds_write_b16 v109, v22 offset:53392
	v_cvt_pk_bf16_f32 v22, v16, s0
	v_mul_f32_e32 v16, v21, v16
	v_cvt_pk_bf16_f32 v16, v16, s0
	ds_write_b16 v109, v16 offset:62752
	v_and_b32_e32 v16, 0xffff0000, v17
	v_mul_f32_e32 v16, v20, v16
	v_cvt_pk_bf16_f32 v17, v16, s0
	v_mul_f32_e32 v16, v21, v16
	v_cvt_pk_bf16_f32 v16, v16, s0
	ds_write_b16 v109, v16 offset:62896
	v_lshlrev_b32_e32 v16, 16, v18
	v_mul_f32_e32 v16, v20, v16
	ds_write_b16 v109, v17 offset:53680
	v_cvt_pk_bf16_f32 v17, v16, s0
	v_mul_f32_e32 v16, v21, v16
	v_cvt_pk_bf16_f32 v16, v16, s0
	ds_write_b16 v109, v16 offset:63040
	v_and_b32_e32 v16, 0xffff0000, v18
	v_mul_f32_e32 v16, v20, v16
	ds_write_b16 v109, v17 offset:53824
	v_cvt_pk_bf16_f32 v17, v16, s0
	v_mul_f32_e32 v16, v21, v16
	v_cvt_pk_bf16_f32 v16, v16, s0
	ds_write_b16 v109, v16 offset:63184
	v_lshlrev_b32_e32 v16, 16, v19
	v_mul_f32_e32 v16, v20, v16
	ds_write_b16 v109, v17 offset:53968
	v_cvt_pk_bf16_f32 v17, v16, s0
	v_mul_f32_e32 v16, v21, v16
	v_cvt_pk_bf16_f32 v16, v16, s0
	ds_write_b16 v109, v16 offset:63328
	v_and_b32_e32 v16, 0xffff0000, v19
	v_mul_f32_e32 v16, v20, v16
	ds_write_b16 v109, v17 offset:54112
	v_cvt_pk_bf16_f32 v17, v16, s0
	v_mul_f32_e32 v16, v21, v16
	v_cvt_pk_bf16_f32 v16, v16, s0
	ds_write_b16 v109, v16 offset:63472
	v_add_co_u32_e32 v16, vcc, 0x1860000, v52
	ds_write_b16 v109, v17 offset:54256
	s_nop 0
	v_addc_co_u32_e32 v17, vcc, 0, v53, vcc
	ds_write_b16 v109, v23 offset:53248
	ds_write_b16 v109, v22 offset:53536
	flat_store_short v[16:17], v151
	v_lshl_add_u64 v[16:17], s[24:25], 0, v[56:57]
	v_lshlrev_b64 v[16:17], 12, v[16:17]
	s_and_saveexec_b64 s[26:27], s[28:29]
	s_cbranch_execz .LBB0_854
	v_lshl_add_u64 v[18:19], s[30:31], 0, v[16:17]
	v_lshl_add_u64 v[18:19], s[34:35], 2, v[18:19]
	flat_store_dword v[18:19], v42 offset:3072
